# R0 ctx rows spread over all workgroups (waves gw%4==0 take row gw/4) instead of workgroups 0..63 only
# speedup vs baseline: 1.0132x; 1.0059x over previous
; __device__ __forceinline__ void unpack8(const u32x4 w, f32x4& a, f32x4& b) { a[0] = bflo(w.x); a[1] = bfhi(w.x); a[2] = bflo(w.y); a[3] = bfhi(w.y); b[0] = bflo(w.z); b[1] = bfhi(w.z); b[2] = bflo(w.w); b[3] = bfhi(w.w); }
; __device__ __forceinline__ void norm_rows_h(const bf16_t* src, bf16_t* dst, int nrows, const f32x4 (&wv)[4], const f32x4 (&shv)[4], int gw, int ngw, int lane) {
;     for (int row0 = gw * 2; row0 < nrows; row0 += ngw * 2) {
;         u32x4 raw[2][2]; f32x4 v[2][4]; float ss[2];
; #pragma unroll
;         for (int rr = 0; rr < 2; ++rr)
; #pragma unroll
;             for (int j = 0; j < 2; ++j) raw[rr][j] = *(const u32x4*)(src + (size_t)(row0 + rr) * D + 8 * lane + 512 * j);
; #pragma unroll
;         for (int rr = 0; rr < 2; ++rr) { float a = 0.f;
; #pragma unroll
;             for (int j = 0; j < 2; ++j) unpack8(raw[rr][j], v[rr][2 * j], v[rr][2 * j + 1]);
; #pragma unroll
;             for (int q = 0; q < 4; ++q) a += (v[rr][q][0] * v[rr][q][0] + v[rr][q][1] * v[rr][q][1]) + (v[rr][q][2] * v[rr][q][2] + v[rr][q][3] * v[rr][q][3]);
;             ss[rr] = a; }
.LBB0_484:
	global_load_dwordx4 v[16:19], v[24:25], off offset:-3072
	global_load_dwordx4 v[38:41], v[24:25], off offset:-2048
	global_load_dwordx4 v[50:53], v[24:25], off offset:-1024
	global_load_dwordx4 v[54:57], v[24:25], off
	s_add_i32 s38, s38, s96
	s_cmpk_lt_i32 s38, 0x4000
	s_waitcnt vmcnt(3)
	v_lshlrev_b32_e32 v74, 16, v16
	v_and_b32_e32 v75, 0xffff0000, v16
	v_mul_f32_e32 v16, v74, v74
	s_waitcnt vmcnt(2)
	v_lshlrev_b32_e32 v42, 16, v40
	v_and_b32_e32 v43, 0xffff0000, v40
	v_lshlrev_b32_e32 v44, 16, v41
	v_and_b32_e32 v45, 0xffff0000, v41
	v_pk_fma_f32 v[40:41], v[74:75], v[74:75], v[16:17] op_sel_hi:[1,1,0]
	v_lshlrev_b32_e32 v16, 16, v17
	v_lshlrev_b32_e32 v77, 16, v19
	v_lshlrev_b32_e32 v76, 16, v18
	v_and_b32_e32 v19, 0xffff0000, v19
	v_and_b32_e32 v18, 0xffff0000, v18
	v_lshlrev_b32_e32 v58, 16, v38
	v_and_b32_e32 v17, 0xffff0000, v17
	v_mul_f32_e32 v46, v16, v16
	v_pk_mul_f32 v[48:49], v[18:19], v[18:19]
	v_and_b32_e32 v59, 0xffff0000, v38
	v_mul_f32_e32 v38, v58, v58
	v_lshlrev_b32_e32 v60, 16, v39
	v_pk_fma_f32 v[46:47], v[16:17], v[16:17], v[46:47] op_sel_hi:[1,1,0]
	v_pk_fma_f32 v[48:49], v[76:77], v[76:77], v[48:49]
	v_pk_fma_f32 v[72:73], v[58:59], v[58:59], v[38:39] op_sel_hi:[1,1,0]
	v_and_b32_e32 v61, 0xffff0000, v39
	v_mul_f32_e32 v38, v60, v60
	v_pk_add_f32 v[48:49], v[48:49], v[48:49] op_sel_hi:[0,1]
	v_pk_fma_f32 v[38:39], v[60:61], v[60:61], v[38:39] op_sel_hi:[1,1,0]
	v_pk_add_f32 v[40:41], v[40:41], v[46:47]
	v_mul_f32_e32 v48, v43, v43
	v_mul_f32_e32 v72, v44, v44
	v_mul_f32_e32 v38, v45, v45
	v_mul_f32_e32 v78, v42, v42
	v_mov_b32_e32 v79, v41
	v_pk_add_f32 v[40:41], v[78:79], v[48:49]
	v_pk_add_f32 v[38:39], v[72:73], v[38:39]
	s_waitcnt vmcnt(1)
	v_lshlrev_b32_e32 v48, 16, v50
	v_pk_add_f32 v[38:39], v[40:41], v[38:39]
	v_and_b32_e32 v49, 0xffff0000, v50
	v_add_f32_e32 v88, v38, v39
	s_waitcnt vmcnt(0)
	v_lshlrev_b32_e32 v38, 16, v56
	v_and_b32_e32 v39, 0xffff0000, v56
	v_mul_f32_e32 v46, v48, v48
	v_lshlrev_b32_e32 v56, 16, v51
	v_lshlrev_b32_e32 v40, 16, v57
	v_and_b32_e32 v41, 0xffff0000, v57
	v_pk_fma_f32 v[72:73], v[48:49], v[48:49], v[46:47] op_sel_hi:[1,1,0]
	v_and_b32_e32 v57, 0xffff0000, v51
	v_mul_f32_e32 v46, v56, v56
	v_lshlrev_b32_e32 v51, 16, v53
	v_lshlrev_b32_e32 v50, 16, v52
	v_and_b32_e32 v53, 0xffff0000, v53
	v_and_b32_e32 v52, 0xffff0000, v52
	v_pk_fma_f32 v[78:79], v[56:57], v[56:57], v[46:47] op_sel_hi:[1,1,0]
	v_pk_mul_f32 v[46:47], v[52:53], v[52:53]
	v_pk_add_f32 v[72:73], v[72:73], v[78:79]
	v_pk_fma_f32 v[46:47], v[50:51], v[50:51], v[46:47]
	v_mul_f32_e32 v86, v38, v38
	v_pk_add_f32 v[80:81], v[46:47], v[46:47] op_sel_hi:[0,1]
	v_lshlrev_b32_e32 v46, 16, v54
	v_and_b32_e32 v47, 0xffff0000, v54
	v_mul_f32_e32 v54, v46, v46
	v_pk_fma_f32 v[82:83], v[46:47], v[46:47], v[54:55] op_sel_hi:[1,1,0]
	v_lshlrev_b32_e32 v54, 16, v55
	v_and_b32_e32 v55, 0xffff0000, v55
	v_mul_f32_e32 v62, v54, v54
	v_pk_fma_f32 v[84:85], v[54:55], v[54:55], v[62:63] op_sel_hi:[1,1,0]
	ds_bpermute_b32 v62, v63, v88
	v_mul_f32_e32 v80, v39, v39
	v_mul_f32_e32 v82, v40, v40
	v_mul_f32_e32 v84, v41, v41
	v_mov_b32_e32 v87, v73
	v_pk_add_f32 v[72:73], v[86:87], v[80:81]
	v_pk_add_f32 v[78:79], v[82:83], v[84:85]
	s_waitcnt lgkmcnt(0)
	v_add_f32_e32 v62, v88, v62
	v_pk_add_f32 v[72:73], v[72:73], v[78:79]
	s_nop 0
	v_add_f32_e32 v72, v72, v73
	ds_bpermute_b32 v73, v64, v62
	s_waitcnt lgkmcnt(0)
	v_add_f32_e32 v62, v62, v73
	ds_bpermute_b32 v73, v65, v62
	s_waitcnt lgkmcnt(0)
	v_add_f32_e32 v62, v62, v73
	ds_bpermute_b32 v73, v66, v62
	s_waitcnt lgkmcnt(0)
	v_add_f32_e32 v62, v62, v73
	ds_bpermute_b32 v73, v70, v62
	s_waitcnt lgkmcnt(0)
	v_add_f32_e32 v62, v62, v73
	ds_bpermute_b32 v73, v71, v62
	s_waitcnt lgkmcnt(0)
; __device__ __forceinline__ u32x4 pack8(const f32x4 a, const f32x4 b) { u32x4 w; w.x = pk2(a[0], a[1]); w.y = pk2(a[2], a[3]); w.z = pk2(b[0], b[1]); w.w = pk2(b[2], b[3]); return w; }
; __device__ __forceinline__ void norm_rows_h(const bf16_t* src, bf16_t* dst, int nrows, const f32x4 (&wv)[4], const f32x4 (&shv)[4], int gw, int ngw, int lane) {
;     ...
; #pragma unroll
;         for (int rr = 0; rr < 2; ++rr) {
;             const float r = rsqrtf(wave_sum(ss[rr], lane) * (1.0f / D) + EPS);
; #pragma unroll
;             for (int j = 0; j < 2; ++j) *(u32x4*)(dst + (size_t)(row0 + rr) * D + 8 * lane + 512 * j) = pack8(v[rr][2 * j] * r * wv[2 * j] + shv[2 * j], v[rr][2 * j + 1] * r * wv[2 * j + 1] + shv[2 * j + 1]);
;         }
;     }
; }
; __device__ __forceinline__ void norm_rows_ctx(const float* cx, const float* slab, bf16_t* dst, int nrows, const f32x4 (&wv)[4], const f32x4 (&shv)[4], int gw, int ngw, int lane) {
;     for (int row = gw; row < nrows; row += ngw) {
	v_add_f32_e32 v62, v62, v73
	v_fmamk_f32 v62, v62, 0x3a800000, v156
	v_cmp_gt_f32_e32 vcc, s13, v62
	v_mul_f32_e32 v73, 0x4b800000, v62
	s_nop 0
	v_cndmask_b32_e32 v62, v62, v73, vcc
	v_rsq_f32_e32 v62, v62
	s_nop 0
	v_mul_f32_e32 v73, 0x45800000, v62
	v_cndmask_b32_e32 v62, v62, v73, vcc
	v_pk_mul_f32 v[74:75], v[62:63], v[74:75] op_sel_hi:[0,1]
	v_pk_mul_f32 v[16:17], v[62:63], v[16:17] op_sel_hi:[0,1]
	v_pk_fma_f32 v[78:79], v[26:27], v[16:17], v[6:7]
	v_pk_fma_f32 v[16:17], v[28:29], v[74:75], v[4:5]
	v_mov_b32_e32 v74, v76
	v_mov_b32_e32 v75, v18
	v_mov_b32_e32 v18, v77
	v_pk_mul_f32 v[74:75], v[62:63], v[74:75] op_sel_hi:[0,1]
	v_pk_mul_f32 v[18:19], v[62:63], v[18:19] op_sel_hi:[0,1]
	v_pk_fma_f32 v[76:77], v[30:31], v[18:19], v[2:3]
	v_pk_fma_f32 v[18:19], v[32:33], v[74:75], v[0:1]
	v_add_co_u32_e32 v74, vcc, s53, v24
	v_cvt_pk_bf16_f32 v16, v16, v17
	v_cvt_pk_bf16_f32 v17, v78, v79
	v_cvt_pk_bf16_f32 v18, v18, v19
	v_cvt_pk_bf16_f32 v19, v76, v77
	s_nop 1
	v_addc_co_u32_e32 v75, vcc, -1, v25, vcc
	global_store_dwordx4 v[74:75], v[16:19], off offset:-3072
	v_pk_mul_f32 v[42:43], v[62:63], v[42:43] op_sel_hi:[0,1]
	v_pk_mul_f32 v[44:45], v[62:63], v[44:45] op_sel_hi:[0,1]
	v_pk_mul_f32 v[16:17], v[62:63], v[58:59] op_sel_hi:[0,1]
	v_pk_mul_f32 v[18:19], v[62:63], v[60:61] op_sel_hi:[0,1]
	v_pk_fma_f32 v[16:17], v[20:21], v[16:17], v[12:13]
	v_pk_fma_f32 v[18:19], v[22:23], v[18:19], v[14:15]
	v_cvt_pk_bf16_f32 v16, v16, v17
	v_pk_fma_f32 v[44:45], v[34:35], v[44:45], v[10:11]
	v_pk_fma_f32 v[42:43], v[36:37], v[42:43], v[8:9]
	v_cvt_pk_bf16_f32 v17, v18, v19
	v_cvt_pk_bf16_f32 v19, v44, v45
	v_mov_b32_e32 v44, v50
	v_cvt_pk_bf16_f32 v18, v42, v43
	global_store_dwordx4 v[74:75], v[16:19], off offset:-2048
	ds_bpermute_b32 v16, v63, v72
	v_mov_b32_e32 v45, v52
	v_mov_b32_e32 v52, v51
	v_lshl_add_u64 v[24:25], v[24:25], 0, s[4:5]
	s_waitcnt lgkmcnt(0)
	v_add_f32_e32 v16, v72, v16
	ds_bpermute_b32 v17, v64, v16
	s_waitcnt lgkmcnt(0)
	v_add_f32_e32 v16, v16, v17
	ds_bpermute_b32 v17, v65, v16
	s_waitcnt lgkmcnt(0)
	v_add_f32_e32 v16, v16, v17
	ds_bpermute_b32 v17, v66, v16
	s_waitcnt lgkmcnt(0)
	v_add_f32_e32 v16, v16, v17
	ds_bpermute_b32 v17, v70, v16
	s_waitcnt lgkmcnt(0)
	v_add_f32_e32 v16, v16, v17
	ds_bpermute_b32 v17, v71, v16
	s_waitcnt lgkmcnt(0)
	v_add_f32_e32 v16, v16, v17
	v_fmamk_f32 v16, v16, 0x3a800000, v156
	v_cmp_gt_f32_e32 vcc, s13, v16
	v_mul_f32_e32 v17, 0x4b800000, v16
	s_nop 0
	v_cndmask_b32_e32 v16, v16, v17, vcc
	v_rsq_f32_e32 v16, v16
	s_nop 0
	v_mul_f32_e32 v17, 0x45800000, v16
	v_cndmask_b32_e32 v42, v16, v17, vcc
	v_pk_mul_f32 v[16:17], v[42:43], v[48:49] op_sel_hi:[0,1]
	v_pk_mul_f32 v[18:19], v[42:43], v[56:57] op_sel_hi:[0,1]
	v_pk_fma_f32 v[18:19], v[26:27], v[18:19], v[6:7]
	v_pk_fma_f32 v[16:17], v[28:29], v[16:17], v[4:5]
	v_pk_mul_f32 v[44:45], v[42:43], v[44:45] op_sel_hi:[0,1]
	v_pk_mul_f32 v[48:49], v[42:43], v[52:53] op_sel_hi:[0,1]
	v_pk_fma_f32 v[48:49], v[30:31], v[48:49], v[2:3]
	v_pk_fma_f32 v[44:45], v[32:33], v[44:45], v[0:1]
	v_cvt_pk_bf16_f32 v16, v16, v17
	v_cvt_pk_bf16_f32 v17, v18, v19
	v_cvt_pk_bf16_f32 v19, v48, v49
	v_pk_mul_f32 v[38:39], v[42:43], v[38:39] op_sel_hi:[0,1]
	v_cvt_pk_bf16_f32 v18, v44, v45
	global_store_dwordx4 v[74:75], v[16:19], off offset:-1024
	v_pk_mul_f32 v[40:41], v[42:43], v[40:41] op_sel_hi:[0,1]
	v_pk_fma_f32 v[40:41], v[34:35], v[40:41], v[10:11]
	v_pk_mul_f32 v[16:17], v[42:43], v[46:47] op_sel_hi:[0,1]
	v_pk_mul_f32 v[18:19], v[42:43], v[54:55] op_sel_hi:[0,1]
	v_pk_fma_f32 v[18:19], v[22:23], v[18:19], v[14:15]
	v_pk_fma_f32 v[16:17], v[20:21], v[16:17], v[12:13]
	v_pk_fma_f32 v[38:39], v[36:37], v[38:39], v[8:9]
	v_cvt_pk_bf16_f32 v16, v16, v17
	v_cvt_pk_bf16_f32 v17, v18, v19
	v_cvt_pk_bf16_f32 v19, v40, v41
	s_nop 0
	v_cvt_pk_bf16_f32 v18, v38, v39
	global_store_dwordx4 v[74:75], v[16:19], off
	s_cbranch_scc1 .LBB0_484
	v_mov_b32_e32 v128, v69
	s_and_b32 s9, s8, 3
	s_lshr_b32 s8, s8, 2
	s_cmp_lg_u32 s9, 0
	s_cselect_b32 s8, 0x200, s8
	s_cmpk_gt_i32 s8, 0x1ff
	s_cbranch_scc1 .LBB0_491
	s_branch .LBB0_489

; __device__ __forceinline__ void norm_rows_ctx(const float* cx, const float* slab, bf16_t* dst, int nrows, const f32x4 (&wv)[4], const f32x4 (&shv)[4], int gw, int ngw, int lane) {
;     for (int row = gw; row < nrows; row += ngw) {
.LBB0_488:
	s_and_b32 s9, s8, 3
	s_lshr_b32 s8, s8, 2
	s_cmp_lg_u32 s9, 0
	s_cselect_b32 s8, 0x200, s8
	s_cmpk_gt_i32 s8, 0x1ff
	s_cbranch_scc1 .LBB0_491
